# grid barrier: buffer_inv sc1 issued early (after XSUB arrival), post-release invs removed; 9th-from-last local arriver issues async pre-clean buffer_wbl2
# speedup vs baseline: 1.0124x; 1.0124x over previous
.LBB0_141:
	s_or_b64 exec, exec, s[8:9]
	v_cvt_f32_u32_e32 v4, v2
	s_waitcnt vmcnt(0)
	buffer_inv sc1
	v_readfirstlane_b32 s6, v3
	v_sub_u32_e32 v3, 0, v2
	v_rcp_iflag_f32_e32 v4, v4
	v_add_u32_e32 v5, s6, v1
	v_mul_f32_e32 v4, 0x4f7ffffe, v4
	v_cvt_u32_f32_e32 v4, v4
	v_mul_lo_u32 v1, v3, v4
	v_mul_hi_u32 v1, v4, v1
	v_add_u32_e32 v1, v4, v1
	v_mul_hi_u32 v1, v5, v1
	v_mul_lo_u32 v3, v1, v2
	v_sub_u32_e32 v3, v5, v3
	v_add_u32_e32 v4, 1, v1
	v_cmp_ge_u32_e32 vcc, v3, v2
	s_nop 1
	v_cndmask_b32_e32 v1, v1, v4, vcc
	v_sub_u32_e32 v4, v3, v2
	v_cndmask_b32_e32 v3, v3, v4, vcc
	v_add_u32_e32 v4, 1, v1
	v_cmp_ge_u32_e32 vcc, v3, v2
	v_add_u32_e32 v3, 1, v5
	s_nop 0
	v_cndmask_b32_e32 v1, v1, v4, vcc
	v_mul_lo_u32 v4, v2, v1
	v_add_u32_e32 v2, v4, v2
	v_add_u32_e32 v4, 8, v3
	v_cmp_eq_u32_e32 vcc, v4, v2
	s_cbranch_vccz .Lnopre_0
	buffer_wbl2 sc1
.Lnopre_0:
	v_cmp_ne_u32_e32 vcc, v3, v2
	s_and_saveexec_b64 s[6:7], vcc
	s_xor_b64 s[6:7], exec, s[6:7]
	s_cbranch_execz .LBB0_155
	s_waitcnt lgkmcnt(0)
	v_mov_b32_e32 v0, 0x2000
	global_load_dword v0, v0, s[4:5] offset:1024 sc1
	s_add_u32 s12, s4, 0x2400
	s_addc_u32 s13, s5, 0
	s_waitcnt vmcnt(0)
	v_cmp_eq_u32_e32 vcc, v0, v1
	s_and_saveexec_b64 s[8:9], vcc
	s_cbranch_execz .LBB0_154
	s_add_u32 s10, s40, 0x4200
	s_addc_u32 s11, s41, 0
	s_mov_b32 s44, 1
	s_mov_b64 s[18:19], 0
	v_mov_b32_e32 v0, 0
	s_branch .LBB0_145

.LBB0_154:
	s_or_b64 exec, exec, s[8:9]
	s_waitcnt vmcnt(0)
	s_waitcnt vmcnt(0)

.LBB0_172:
	s_or_b64 exec, exec, s[6:7]
	s_mov_b64 s[6:7], exec
	v_mbcnt_lo_u32_b32 v0, s6, 0
	v_mbcnt_hi_u32_b32 v0, s7, v0
	v_cmp_eq_u32_e32 vcc, 0, v0
	s_and_saveexec_b64 s[8:9], vcc
	s_cbranch_execz .LBB0_174
	s_bcnt1_i32_b64 s6, s[6:7]
	v_mov_b32_e32 v0, 0x2000
	v_mov_b32_e32 v1, s6
	global_atomic_add v0, v1, s[4:5] offset:1024

.Lnopre_1:
	v_cmp_ne_u32_e32 vcc, v3, v2
	s_and_saveexec_b64 s[6:7], vcc
	s_xor_b64 s[6:7], exec, s[6:7]
	s_cbranch_execz .LBB0_223
	s_waitcnt lgkmcnt(0)
	v_mov_b32_e32 v0, 0x2000
	global_load_dword v0, v0, s[4:5] offset:1024 sc1
	s_add_u32 s12, s4, 0x2400
	s_addc_u32 s13, s5, 0
	s_waitcnt vmcnt(0)
	v_cmp_eq_u32_e32 vcc, v0, v1
	s_and_saveexec_b64 s[8:9], vcc
	s_cbranch_execz .LBB0_222
	s_add_u32 s10, s40, 0x4200
	s_addc_u32 s11, s41, 0
	s_mov_b32 s48, 1
	s_mov_b64 s[24:25], 0
	v_mov_b32_e32 v0, 0
	s_branch .LBB0_213

.Lnopre_2:
	v_cmp_ne_u32_e32 vcc, v3, v2
	s_and_saveexec_b64 s[6:7], vcc
	s_xor_b64 s[6:7], exec, s[6:7]
	s_cbranch_execz .LBB0_303
	s_waitcnt lgkmcnt(0)
	v_mov_b32_e32 v0, 0x2000
	global_load_dword v0, v0, s[4:5] offset:1024 sc1
	s_add_u32 s30, s4, 0x2400
	s_addc_u32 s31, s5, 0
	s_waitcnt vmcnt(0)
	v_cmp_eq_u32_e32 vcc, v0, v1
	s_and_saveexec_b64 s[8:9], vcc
	s_cbranch_execz .LBB0_302
	s_add_u32 s10, s40, 0x4200
	s_addc_u32 s11, s41, 0
	s_mov_b32 s54, 1
	s_mov_b64 s[36:37], 0
	v_mov_b32_e32 v0, 0
	s_branch .LBB0_293

.Lnopre_3:
	v_cmp_ne_u32_e32 vcc, v3, v2
	s_and_saveexec_b64 s[6:7], vcc
	s_xor_b64 s[6:7], exec, s[6:7]
	s_cbranch_execz .LBB0_358
	s_waitcnt lgkmcnt(0)
	v_mov_b32_e32 v0, 0x2000
	global_load_dword v0, v0, s[4:5] offset:1024 sc1
	s_add_u32 s16, s4, 0x2400
	s_addc_u32 s17, s5, 0
	s_waitcnt vmcnt(0)
	v_cmp_eq_u32_e32 vcc, v0, v1
	s_and_saveexec_b64 s[8:9], vcc
	s_cbranch_execz .LBB0_357
	s_add_u32 s10, s40, 0x4200
	s_addc_u32 s11, s41, 0
	s_mov_b32 s54, 1
	s_mov_b64 s[36:37], 0
	v_mov_b32_e32 v0, 0
	s_branch .LBB0_348

.LBB0_481:
	s_or_b64 exec, exec, s[16:17]
	v_cvt_f32_u32_e32 v4, v2
	s_waitcnt vmcnt(0)
	buffer_inv sc1
	v_readfirstlane_b32 s6, v3
	v_sub_u32_e32 v3, 0, v2
	v_rcp_iflag_f32_e32 v4, v4
	v_add_u32_e32 v5, s6, v1
	v_mul_f32_e32 v4, 0x4f7ffffe, v4
	v_cvt_u32_f32_e32 v4, v4
	v_mul_lo_u32 v1, v3, v4
	v_mul_hi_u32 v1, v4, v1
	v_add_u32_e32 v1, v4, v1
	v_mul_hi_u32 v1, v5, v1
	v_mul_lo_u32 v3, v1, v2
	v_sub_u32_e32 v3, v5, v3
	v_add_u32_e32 v4, 1, v1
	v_cmp_ge_u32_e32 vcc, v3, v2
	s_nop 1
	v_cndmask_b32_e32 v1, v1, v4, vcc
	v_sub_u32_e32 v4, v3, v2
	v_cndmask_b32_e32 v3, v3, v4, vcc
	v_add_u32_e32 v4, 1, v1
	v_cmp_ge_u32_e32 vcc, v3, v2
	v_add_u32_e32 v3, 1, v5
	s_nop 0
	v_cndmask_b32_e32 v1, v1, v4, vcc
	v_mul_lo_u32 v4, v2, v1
	v_add_u32_e32 v2, v4, v2
	v_add_u32_e32 v4, 8, v3
	v_cmp_eq_u32_e32 vcc, v4, v2
	s_cbranch_vccz .Lnopre_5
	buffer_wbl2 sc1
.Lnopre_5:
	v_cmp_ne_u32_e32 vcc, v3, v2
	s_and_saveexec_b64 s[6:7], vcc
	s_xor_b64 s[6:7], exec, s[6:7]
	s_cbranch_execz .LBB0_495
	s_waitcnt lgkmcnt(0)
	v_mov_b32_e32 v0, 0x2000
	global_load_dword v0, v0, s[4:5] offset:1024 sc1
	s_add_u32 s44, s4, 0x2400
	s_addc_u32 s45, s5, 0
	s_waitcnt vmcnt(0)
	v_cmp_eq_u32_e32 vcc, v0, v1
	s_and_saveexec_b64 s[16:17], vcc
	s_cbranch_execz .LBB0_494
	s_add_u32 s36, s40, 0x4200
	s_addc_u32 s37, s41, 0
	s_mov_b32 s58, 1
	s_mov_b64 s[46:47], 0
	v_mov_b32_e32 v0, 0
	s_branch .LBB0_485

.LBB0_494:
	s_or_b64 exec, exec, s[16:17]
	s_waitcnt vmcnt(0)
	s_waitcnt vmcnt(0)

.LBB0_512:
	s_or_b64 exec, exec, s[6:7]
	s_mov_b64 s[6:7], exec
	v_mbcnt_lo_u32_b32 v0, s6, 0
	v_mbcnt_hi_u32_b32 v0, s7, v0
	v_cmp_eq_u32_e32 vcc, 0, v0
	s_and_saveexec_b64 s[16:17], vcc
	s_cbranch_execz .LBB0_514
	s_bcnt1_i32_b64 s6, s[6:7]
	v_mov_b32_e32 v0, 0x2000
	v_mov_b32_e32 v1, s6
	global_atomic_add v0, v1, s[4:5] offset:1024

.LBB0_626:
	s_or_b64 exec, exec, s[10:11]
	v_cvt_f32_u32_e32 v4, v2
	s_waitcnt vmcnt(0)
	buffer_inv sc1
	v_readfirstlane_b32 s8, v3
	v_sub_u32_e32 v3, 0, v2
	v_rcp_iflag_f32_e32 v4, v4
	v_add_u32_e32 v5, s8, v1
	v_mul_f32_e32 v4, 0x4f7ffffe, v4
	v_cvt_u32_f32_e32 v4, v4
	v_mul_lo_u32 v1, v3, v4
	v_mul_hi_u32 v1, v4, v1
	v_add_u32_e32 v1, v4, v1
	v_mul_hi_u32 v1, v5, v1
	v_mul_lo_u32 v3, v1, v2
	v_sub_u32_e32 v3, v5, v3
	v_add_u32_e32 v4, 1, v1
	v_cmp_ge_u32_e32 vcc, v3, v2
	s_nop 1
	v_cndmask_b32_e32 v1, v1, v4, vcc
	v_sub_u32_e32 v4, v3, v2
	v_cndmask_b32_e32 v3, v3, v4, vcc
	v_add_u32_e32 v4, 1, v1
	v_cmp_ge_u32_e32 vcc, v3, v2
	v_add_u32_e32 v3, 1, v5
	s_nop 0
	v_cndmask_b32_e32 v1, v1, v4, vcc
	v_mul_lo_u32 v4, v2, v1
	v_add_u32_e32 v2, v4, v2
	v_add_u32_e32 v4, 8, v3
	v_cmp_eq_u32_e32 vcc, v4, v2
	s_cbranch_vccz .Lnopre_7
	buffer_wbl2 sc1
.Lnopre_7:
	v_cmp_ne_u32_e32 vcc, v3, v2
	s_and_saveexec_b64 s[8:9], vcc
	s_xor_b64 s[8:9], exec, s[8:9]
	s_cbranch_execz .LBB0_640
	s_waitcnt lgkmcnt(0)
	v_mov_b32_e32 v0, 0x2000
	global_load_dword v0, v0, s[4:5] offset:1024 sc1
	s_add_u32 s16, s4, 0x2400
	s_addc_u32 s17, s5, 0
	s_waitcnt vmcnt(0)
	v_cmp_eq_u32_e32 vcc, v0, v1
	s_and_saveexec_b64 s[10:11], vcc
	s_cbranch_execz .LBB0_639
	s_add_u32 s12, s40, 0x4200
	s_addc_u32 s13, s41, 0
	s_mov_b32 s54, 1
	s_mov_b64 s[36:37], 0
	v_mov_b32_e32 v0, 0
	s_branch .LBB0_630

.LBB0_639:
	s_or_b64 exec, exec, s[10:11]
	s_waitcnt vmcnt(0)
	s_waitcnt vmcnt(0)

.LBB0_657:
	s_or_b64 exec, exec, s[8:9]
	s_mov_b64 s[8:9], exec
	v_mbcnt_lo_u32_b32 v0, s8, 0
	v_mbcnt_hi_u32_b32 v0, s9, v0
	v_cmp_eq_u32_e32 vcc, 0, v0
	s_and_saveexec_b64 s[10:11], vcc
	s_cbranch_execz .LBB0_659
	s_bcnt1_i32_b64 s8, s[8:9]
	v_mov_b32_e32 v0, 0x2000
	v_mov_b32_e32 v1, s8
	global_atomic_add v0, v1, s[4:5] offset:1024

.LBB0_681:
	s_or_b64 exec, exec, s[12:13]
	v_cvt_f32_u32_e32 v4, v2
	s_waitcnt vmcnt(0)
	buffer_inv sc1
	v_readfirstlane_b32 s10, v3
	v_sub_u32_e32 v3, 0, v2
	v_rcp_iflag_f32_e32 v4, v4
	v_add_u32_e32 v5, s10, v1
	v_mul_f32_e32 v4, 0x4f7ffffe, v4
	v_cvt_u32_f32_e32 v4, v4
	v_mul_lo_u32 v1, v3, v4
	v_mul_hi_u32 v1, v4, v1
	v_add_u32_e32 v1, v4, v1
	v_mul_hi_u32 v1, v5, v1
	v_mul_lo_u32 v3, v1, v2
	v_sub_u32_e32 v3, v5, v3
	v_add_u32_e32 v4, 1, v1
	v_cmp_ge_u32_e32 vcc, v3, v2
	s_nop 1
	v_cndmask_b32_e32 v1, v1, v4, vcc
	v_sub_u32_e32 v4, v3, v2
	v_cndmask_b32_e32 v3, v3, v4, vcc
	v_add_u32_e32 v4, 1, v1
	v_cmp_ge_u32_e32 vcc, v3, v2
	v_add_u32_e32 v3, 1, v5
	s_nop 0
	v_cndmask_b32_e32 v1, v1, v4, vcc
	v_mul_lo_u32 v4, v2, v1
	v_add_u32_e32 v2, v4, v2
	v_add_u32_e32 v4, 8, v3
	v_cmp_eq_u32_e32 vcc, v4, v2
	s_cbranch_vccz .Lnopre_8
	buffer_wbl2 sc1
.Lnopre_8:
	v_cmp_ne_u32_e32 vcc, v3, v2
	s_and_saveexec_b64 s[10:11], vcc
	s_xor_b64 s[10:11], exec, s[10:11]
	s_cbranch_execz .LBB0_695
	s_waitcnt lgkmcnt(0)
	v_mov_b32_e32 v0, 0x2000
	global_load_dword v0, v0, s[8:9] offset:1024 sc1
	s_add_u32 s30, s8, 0x2400
	s_addc_u32 s31, s9, 0
	s_waitcnt vmcnt(0)
	v_cmp_eq_u32_e32 vcc, v0, v1
	s_and_saveexec_b64 s[12:13], vcc
	s_cbranch_execz .LBB0_694
	s_add_u32 s16, s40, 0x4200
	s_addc_u32 s17, s41, 0
	s_mov_b32 s54, 1
	s_mov_b64 s[36:37], 0
	v_mov_b32_e32 v0, 0
	s_branch .LBB0_685

.LBB0_694:
	s_or_b64 exec, exec, s[12:13]
	s_waitcnt vmcnt(0)
	s_waitcnt vmcnt(0)

.LBB0_712:
	s_or_b64 exec, exec, s[10:11]
	s_mov_b64 s[10:11], exec
	v_mbcnt_lo_u32_b32 v0, s10, 0
	v_mbcnt_hi_u32_b32 v0, s11, v0
	v_cmp_eq_u32_e32 vcc, 0, v0
	s_and_saveexec_b64 s[12:13], vcc
	s_cbranch_execz .LBB0_714
	s_bcnt1_i32_b64 s10, s[10:11]
	v_mov_b32_e32 v0, 0x2000
	v_mov_b32_e32 v1, s10
	global_atomic_add v0, v1, s[8:9] offset:1024

.LBB0_749:
	s_or_b64 exec, exec, s[16:17]
	v_cvt_f32_u32_e32 v4, v2
	s_waitcnt vmcnt(0)
	buffer_inv sc1
	v_readfirstlane_b32 s12, v3
	v_sub_u32_e32 v3, 0, v2
	v_rcp_iflag_f32_e32 v4, v4
	v_add_u32_e32 v5, s12, v1
	v_mul_f32_e32 v4, 0x4f7ffffe, v4
	v_cvt_u32_f32_e32 v4, v4
	v_mul_lo_u32 v1, v3, v4
	v_mul_hi_u32 v1, v4, v1
	v_add_u32_e32 v1, v4, v1
	v_mul_hi_u32 v1, v5, v1
	v_mul_lo_u32 v3, v1, v2
	v_sub_u32_e32 v3, v5, v3
	v_add_u32_e32 v4, 1, v1
	v_cmp_ge_u32_e32 vcc, v3, v2
	s_nop 1
	v_cndmask_b32_e32 v1, v1, v4, vcc
	v_sub_u32_e32 v4, v3, v2
	v_cndmask_b32_e32 v3, v3, v4, vcc
	v_add_u32_e32 v4, 1, v1
	v_cmp_ge_u32_e32 vcc, v3, v2
	v_add_u32_e32 v3, 1, v5
	s_nop 0
	v_cndmask_b32_e32 v1, v1, v4, vcc
	v_mul_lo_u32 v4, v2, v1
	v_add_u32_e32 v2, v4, v2
	v_add_u32_e32 v4, 8, v3
	v_cmp_eq_u32_e32 vcc, v4, v2
	s_cbranch_vccz .Lnopre_9
	buffer_wbl2 sc1
.Lnopre_9:
	v_cmp_ne_u32_e32 vcc, v3, v2
	s_and_saveexec_b64 s[12:13], vcc
	s_xor_b64 s[12:13], exec, s[12:13]
	s_cbranch_execz .LBB0_763
	s_waitcnt lgkmcnt(0)
	v_mov_b32_e32 v0, 0x2000
	global_load_dword v0, v0, s[10:11] offset:1024 sc1
	s_add_u32 s30, s10, 0x2400
	s_addc_u32 s31, s11, 0
	s_waitcnt vmcnt(0)
	v_cmp_eq_u32_e32 vcc, v0, v1
	s_and_saveexec_b64 s[16:17], vcc
	s_cbranch_execz .LBB0_762
	s_add_u32 s18, s40, 0x4200
	s_addc_u32 s19, s41, 0
	s_mov_b32 s54, 1
	s_mov_b64 s[36:37], 0
	v_mov_b32_e32 v0, 0
	s_branch .LBB0_753

.LBB0_780:
	s_or_b64 exec, exec, s[12:13]
	s_mov_b64 s[12:13], exec
	v_mbcnt_lo_u32_b32 v0, s12, 0
	v_mbcnt_hi_u32_b32 v0, s13, v0
	v_cmp_eq_u32_e32 vcc, 0, v0
	s_and_saveexec_b64 s[16:17], vcc
	s_cbranch_execz .LBB0_782
	s_bcnt1_i32_b64 s12, s[12:13]
	v_mov_b32_e32 v0, 0x2000
	v_mov_b32_e32 v1, s12
	global_atomic_add v0, v1, s[10:11] offset:1024

.Lnopre_12:
	v_cmp_ne_u32_e32 vcc, v3, v2
	s_and_saveexec_b64 s[12:13], vcc
	s_xor_b64 s[12:13], exec, s[12:13]
	s_cbranch_execz .LBB0_990
	s_waitcnt lgkmcnt(0)
	v_mov_b32_e32 v0, 0x2000
	global_load_dword v0, v0, s[10:11] offset:1024 sc1
	s_add_u32 s36, s10, 0x2400
	s_addc_u32 s37, s11, 0
	s_waitcnt vmcnt(0)
	v_cmp_eq_u32_e32 vcc, v0, v1
	s_and_saveexec_b64 s[16:17], vcc
	s_cbranch_execz .LBB0_989
	s_add_u32 s18, s40, 0x4200
	s_addc_u32 s19, s41, 0
	s_mov_b32 s56, 1
	s_mov_b64 s[44:45], 0
	v_mov_b32_e32 v0, 0
	s_branch .LBB0_980

.Lnopre_16:
	v_cmp_ne_u32_e32 vcc, v3, v2
	s_and_saveexec_b64 s[12:13], vcc
	s_xor_b64 s[12:13], exec, s[12:13]
	s_cbranch_execz .LBB0_1274
	s_waitcnt lgkmcnt(0)
	v_mov_b32_e32 v0, 0x2000
	global_load_dword v0, v0, s[10:11] offset:1024 sc1
	s_add_u32 s30, s10, 0x2400
	s_addc_u32 s31, s11, 0
	s_waitcnt vmcnt(0)
	v_cmp_eq_u32_e32 vcc, v0, v1
	s_and_saveexec_b64 s[16:17], vcc
	s_cbranch_execz .LBB0_1273
	s_add_u32 s18, s40, 0x4200
	s_addc_u32 s19, s41, 0
	s_mov_b32 s52, 1
	s_mov_b64 s[36:37], 0
	v_mov_b32_e32 v0, 0
	s_branch .LBB0_1264

.Lnopre_19:
	v_cmp_ne_u32_e32 vcc, v3, v2
	s_and_saveexec_b64 s[10:11], vcc
	s_xor_b64 s[10:11], exec, s[10:11]
	s_cbranch_execz .LBB0_1473
	s_waitcnt lgkmcnt(0)
	v_mov_b32_e32 v0, 0x2000
	global_load_dword v0, v0, s[8:9] offset:1024 sc1
	s_add_u32 s18, s8, 0x2400
	s_addc_u32 s19, s9, 0
	s_waitcnt vmcnt(0)
	v_cmp_eq_u32_e32 vcc, v0, v1
	s_and_saveexec_b64 s[12:13], vcc
	s_cbranch_execz .LBB0_1472
	s_add_u32 s16, s40, 0x4200
	s_addc_u32 s17, s41, 0
	s_mov_b32 s50, 1
	s_mov_b64 s[30:31], 0
	v_mov_b32_e32 v0, 0
	s_branch .LBB0_1463

.Lnopre_20:
	v_cmp_ne_u32_e32 vcc, v3, v2
	s_and_saveexec_b64 s[6:7], vcc
	s_xor_b64 s[6:7], exec, s[6:7]
	s_cbranch_execz .LBB0_1553
	s_waitcnt lgkmcnt(0)
	v_mov_b32_e32 v0, 0x2000
	global_load_dword v0, v0, s[2:3] offset:1024 sc1
	s_add_u32 s12, s2, 0x2400
	s_addc_u32 s13, s3, 0
	s_waitcnt vmcnt(0)
	v_cmp_eq_u32_e32 vcc, v0, v1
	s_and_saveexec_b64 s[8:9], vcc
	s_cbranch_execz .LBB0_1552
	s_add_u32 s10, s40, 0x4200
	s_addc_u32 s11, s41, 0
	s_mov_b32 s24, 1
	s_mov_b64 s[14:15], 0
	v_mov_b32_e32 v0, 0
	s_branch .LBB0_1543

.LBB0_1570:
	s_or_b64 exec, exec, s[6:7]
	s_mov_b64 s[6:7], exec
	v_mbcnt_lo_u32_b32 v0, s6, 0
	v_mbcnt_hi_u32_b32 v0, s7, v0
	v_cmp_eq_u32_e32 vcc, 0, v0
	s_and_saveexec_b64 s[8:9], vcc
	s_cbranch_execz .LBB0_1572
	s_bcnt1_i32_b64 s6, s[6:7]
	v_mov_b32_e32 v0, 0x2000
	v_mov_b32_e32 v1, s6
	global_atomic_add v0, v1, s[2:3] offset:1024
